# G1: half the workgroups run the skinny gate-column pass before the GEMM instead of after (free stagger)
# baseline (speedup 1.0000x reference)
; __global__ __launch_bounds__(512, 2) void mk_fwd(Params p) {
;     ...
;     if (RUN(1)) {
;         pg8::PanelOrder S{(int)blockIdx.x, 12};
;         pg8::EpiP0 E{P0, (float*)(p.ws + OFF_GATES)};
;         pg8::gemm_phase(lds, pg8::Gemm{XB, (const bf16_t*)(p.ws + OFF_WT0), MTOK, 3072, 1024, 1024}, S, E);
;         panel_gates(XB, (const bf16_t*)(p.ws + OFF_WT0) + (size_t)3072 * 1024, (float*)(p.ws + OFF_GATES), (int)blockIdx.x * 256);
;     }
.LBB0_69:
	s_cmp_lt_i32 s80, 2
	s_cselect_b64 s[0:1], -1, 0
	s_and_b64 s[4:5], s[0:1], s[8:9]
	s_andn2_b64 vcc, exec, s[4:5]
	s_cbranch_vccnz .LBB0_79
	s_mov_b32 s99, 0
	s_bitcmp1_b32 s2, 3
	s_cbranch_scc0 .Lg1_gemm
	s_mov_b32 s99, 1
	s_lshl_b32 s27, s2, 8
	v_mov_b32_e32 v6, v176
	s_branch .Lg1_gates

; __device__ void panel_gates(const bf16_t* XB, const bf16_t* Wg  , float* gates, int r0) {
;     int tid = threadIdx.x; asm volatile("" : "+v"(tid));
;     const int wid = tid >> 6, lane = tid & 63, li = lane & 15, kq = lane >> 4;
;     const bf16_t* xa = XB + (size_t)(r0 + (2 * wid) * 16 + li) * 1024 + kq * 8;
;     const bf16_t* xb = xa + 16 * 1024;
;     const bf16_t* wp = Wg + (size_t)li * 1024 + kq * 8;
;     f32x4 acc0 = {0.f, 0.f, 0.f, 0.f}, acc1 = {0.f, 0.f, 0.f, 0.f};
;     for (int kc = 0; kc < 4; ++kc) {
;         bf16x8 wf[8], x0[8], x1[8];
; #pragma unroll
;         for (int u = 0; u < 8; ++u) { const int ko = (kc * 8 + u) * 32; wf[u] = *(const bf16x8*)(wp + ko); x0[u] = *(const bf16x8*)(xa + ko); x1[u] = *(const bf16x8*)(xb + ko); }
; #pragma unroll
;         for (int u = 0; u < 8; ++u) { acc0 = __builtin_amdgcn_mfma_f32_16x16x32_bf16(wf[u], x0[u], acc0, 0, 0, 0); acc1 = __builtin_amdgcn_mfma_f32_16x16x32_bf16(wf[u], x1[u], acc1, 0, 0, 0); }
;     }
;     *(f32x4*)(gates + (size_t)(r0 + (2 * wid) * 16 + li) * 16 + kq * 4) = acc0;
;     *(f32x4*)(gates + (size_t)(r0 + (2 * wid + 1) * 16 + li) * 16 + kq * 4) = acc1;
; }
.LBB0_78:
	v_mov_b32_e32 v6, v176
	s_barrier
	s_cmp_eq_u32 s99, 2
	s_cbranch_scc1 .LBB0_79
.Lg1_gates:
	s_mov_b64 s[4:5], 0x18600000
	v_and_b32_e32 v7, 15, v6
	v_ashrrev_i32_e32 v0, 1, v6
	v_and_b32_e32 v0, 0xffffffe0, v0
	v_or_b32_e32 v1, s27, v7
	v_add_u32_e32 v2, v1, v0
	v_ashrrev_i32_e32 v3, 31, v2
	v_lshlrev_b64 v[0:1], 11, v[2:3]
	v_lshl_add_u64 v[4:5], s[76:77], 0, v[0:1]
	v_mov_b32_e32 v1, 0
	v_and_b32_e32 v0, 48, v6
	v_lshlrev_b32_e32 v6, 11, v7
	v_mov_b32_e32 v7, v1
	v_lshl_add_u64 v[6:7], s[78:79], 0, v[6:7]
	v_lshl_add_u64 v[8:9], v[6:7], 0, v[0:1]
	s_mov_b32 s3, 0x18600000
	v_lshl_add_u64 v[6:7], v[8:9], 0, s[4:5]
	v_add_co_u32_e32 v8, vcc, s3, v8
	v_lshl_add_u64 v[4:5], v[4:5], 0, v[0:1]
	s_nop 0
	v_addc_co_u32_e32 v9, vcc, 0, v9, vcc
	global_load_dwordx4 v[10:13], v[8:9], off
	global_load_dwordx4 v[14:17], v[4:5], off
	s_mov_b32 s3, 0x8000
	v_add_co_u32_e32 v8, vcc, s3, v4
	s_add_u32 s4, s78, 0x18fe0000
	s_nop 0
	v_addc_co_u32_e32 v9, vcc, 0, v5, vcc
	global_load_dwordx4 v[18:21], v[8:9], off
	global_load_dwordx4 v[22:25], v[6:7], off offset:64
	global_load_dwordx4 v[26:29], v[4:5], off offset:64
	global_load_dwordx4 v[30:33], v[8:9], off offset:64
	global_load_dwordx4 v[34:37], v[6:7], off offset:128
	global_load_dwordx4 v[38:41], v[4:5], off offset:128
	global_load_dwordx4 v[42:45], v[8:9], off offset:128
	global_load_dwordx4 v[46:49], v[6:7], off offset:192
	global_load_dwordx4 v[50:53], v[4:5], off offset:192
	global_load_dwordx4 v[54:57], v[6:7], off offset:256
	global_load_dwordx4 v[58:61], v[8:9], off offset:192
	global_load_dwordx4 v[62:65], v[4:5], off offset:256
	global_load_dwordx4 v[66:69], v[6:7], off offset:320
	global_load_dwordx4 v[70:73], v[6:7], off offset:1984
	global_load_dwordx4 v[74:77], v[8:9], off offset:256
	s_addc_u32 s5, s79, 0
	s_waitcnt vmcnt(0)
	v_mfma_f32_16x16x32_bf16 v[14:17], v[10:13], v[14:17], 0
	v_mfma_f32_16x16x32_bf16 v[10:13], v[10:13], v[18:21], 0
	global_load_dwordx4 v[18:21], v[4:5], off offset:320
	global_load_dwordx4 v[78:81], v[6:7], off offset:384
	v_mfma_f32_16x16x32_bf16 v[14:17], v[22:25], v[26:29], v[14:17]
	global_load_dwordx4 v[26:29], v[8:9], off offset:320
	v_mfma_f32_16x16x32_bf16 v[10:13], v[22:25], v[30:33], v[10:13]
	global_load_dwordx4 v[22:25], v[4:5], off offset:384
	global_load_dwordx4 v[30:33], v[6:7], off offset:448
	v_mfma_f32_16x16x32_bf16 v[14:17], v[34:37], v[38:41], v[14:17]
	global_load_dwordx4 v[38:41], v[8:9], off offset:384
	v_mfma_f32_16x16x32_bf16 v[10:13], v[34:37], v[42:45], v[10:13]
	global_load_dwordx4 v[34:37], v[4:5], off offset:448
	global_load_dwordx4 v[42:45], v[6:7], off offset:512
	v_mfma_f32_16x16x32_bf16 v[14:17], v[46:49], v[50:53], v[14:17]
	global_load_dwordx4 v[50:53], v[8:9], off offset:448
	v_mfma_f32_16x16x32_bf16 v[10:13], v[46:49], v[58:61], v[10:13]
	global_load_dwordx4 v[46:49], v[4:5], off offset:512
	global_load_dwordx4 v[58:61], v[6:7], off offset:576
	v_mfma_f32_16x16x32_bf16 v[14:17], v[54:57], v[62:65], v[14:17]
	global_load_dwordx4 v[62:65], v[8:9], off offset:512
	v_mfma_f32_16x16x32_bf16 v[10:13], v[54:57], v[74:77], v[10:13]
	global_load_dwordx4 v[54:57], v[4:5], off offset:576
	global_load_dwordx4 v[74:77], v[6:7], off offset:640
	s_waitcnt vmcnt(0)
	v_mfma_f32_16x16x32_bf16 v[14:17], v[66:69], v[18:21], v[14:17]
	global_load_dwordx4 v[18:21], v[8:9], off offset:576
	v_mfma_f32_16x16x32_bf16 v[10:13], v[66:69], v[26:29], v[10:13]
	global_load_dwordx4 v[26:29], v[4:5], off offset:640
	v_mfma_f32_16x16x32_bf16 v[14:17], v[78:81], v[22:25], v[14:17]
	global_load_dwordx4 v[22:25], v[8:9], off offset:640
	v_mfma_f32_16x16x32_bf16 v[10:13], v[78:81], v[38:41], v[10:13]
	global_load_dwordx4 v[38:41], v[6:7], off offset:704
	v_mfma_f32_16x16x32_bf16 v[14:17], v[30:33], v[34:37], v[14:17]
	global_load_dwordx4 v[34:37], v[4:5], off offset:704
	global_load_dwordx4 v[66:69], v[8:9], off offset:704
	v_mfma_f32_16x16x32_bf16 v[10:13], v[30:33], v[50:53], v[10:13]
	global_load_dwordx4 v[30:33], v[6:7], off offset:768
	v_mfma_f32_16x16x32_bf16 v[14:17], v[42:45], v[46:49], v[14:17]
	global_load_dwordx4 v[46:49], v[4:5], off offset:768
	global_load_dwordx4 v[50:53], v[6:7], off offset:832
	v_mfma_f32_16x16x32_bf16 v[10:13], v[42:45], v[62:65], v[10:13]
	global_load_dwordx4 v[42:45], v[8:9], off offset:768
	v_mfma_f32_16x16x32_bf16 v[14:17], v[58:61], v[54:57], v[14:17]
	global_load_dwordx4 v[54:57], v[4:5], off offset:832
	global_load_dwordx4 v[62:65], v[6:7], off offset:896
	s_waitcnt vmcnt(0)
	v_mfma_f32_16x16x32_bf16 v[10:13], v[58:61], v[18:21], v[10:13]
	global_load_dwordx4 v[18:21], v[8:9], off offset:832
	v_mfma_f32_16x16x32_bf16 v[14:17], v[74:77], v[26:29], v[14:17]
	global_load_dwordx4 v[26:29], v[4:5], off offset:896
	v_mfma_f32_16x16x32_bf16 v[10:13], v[74:77], v[22:25], v[10:13]
	global_load_dwordx4 v[22:25], v[8:9], off offset:896
	v_mfma_f32_16x16x32_bf16 v[14:17], v[38:41], v[34:37], v[14:17]
	global_load_dwordx4 v[34:37], v[6:7], off offset:960
	v_mfma_f32_16x16x32_bf16 v[10:13], v[38:41], v[66:69], v[10:13]
	global_load_dwordx4 v[38:41], v[4:5], off offset:960
	global_load_dwordx4 v[58:61], v[8:9], off offset:960
	v_mfma_f32_16x16x32_bf16 v[14:17], v[30:33], v[46:49], v[14:17]
	global_load_dwordx4 v[46:49], v[6:7], off offset:1024
	v_mfma_f32_16x16x32_bf16 v[10:13], v[30:33], v[42:45], v[10:13]
	global_load_dwordx4 v[30:33], v[4:5], off offset:1024
	global_load_dwordx4 v[42:45], v[6:7], off offset:1088
	v_mfma_f32_16x16x32_bf16 v[14:17], v[50:53], v[54:57], v[14:17]
	global_load_dwordx4 v[54:57], v[8:9], off offset:1024
	s_waitcnt vmcnt(0)
; __device__ void panel_gates(const bf16_t* XB, const bf16_t* Wg  , float* gates, int r0) {
;     ...
;     for (int kc = 0; kc < 4; ++kc) {
;         bf16x8 wf[8], x0[8], x1[8];
; #pragma unroll
;         for (int u = 0; u < 8; ++u) { const int ko = (kc * 8 + u) * 32; wf[u] = *(const bf16x8*)(wp + ko); x0[u] = *(const bf16x8*)(xa + ko); x1[u] = *(const bf16x8*)(xb + ko); }
; #pragma unroll
;         for (int u = 0; u < 8; ++u) { acc0 = __builtin_amdgcn_mfma_f32_16x16x32_bf16(wf[u], x0[u], acc0, 0, 0, 0); acc1 = __builtin_amdgcn_mfma_f32_16x16x32_bf16(wf[u], x1[u], acc1, 0, 0, 0); }
;     }
;     *(f32x4*)(gates + (size_t)(r0 + (2 * wid) * 16 + li) * 16 + kq * 4) = acc0;
;     *(f32x4*)(gates + (size_t)(r0 + (2 * wid + 1) * 16 + li) * 16 + kq * 4) = acc1;
	v_mfma_f32_16x16x32_bf16 v[10:13], v[50:53], v[18:21], v[10:13]
	global_load_dwordx4 v[18:21], v[4:5], off offset:1088
	global_load_dwordx4 v[50:53], v[6:7], off offset:1152
	v_mfma_f32_16x16x32_bf16 v[14:17], v[62:65], v[26:29], v[14:17]
	global_load_dwordx4 v[26:29], v[8:9], off offset:1088
	v_mfma_f32_16x16x32_bf16 v[10:13], v[62:65], v[22:25], v[10:13]
	global_load_dwordx4 v[22:25], v[4:5], off offset:1152
	global_load_dwordx4 v[62:65], v[6:7], off offset:1216
	v_mfma_f32_16x16x32_bf16 v[14:17], v[34:37], v[38:41], v[14:17]
	global_load_dwordx4 v[38:41], v[8:9], off offset:1152
	v_mfma_f32_16x16x32_bf16 v[10:13], v[34:37], v[58:61], v[10:13]
	global_load_dwordx4 v[34:37], v[4:5], off offset:1216
	global_load_dwordx4 v[58:61], v[6:7], off offset:1280
	v_mfma_f32_16x16x32_bf16 v[14:17], v[46:49], v[30:33], v[14:17]
	global_load_dwordx4 v[30:33], v[8:9], off offset:1216
	v_mfma_f32_16x16x32_bf16 v[10:13], v[46:49], v[54:57], v[10:13]
	global_load_dwordx4 v[46:49], v[4:5], off offset:1280
	global_load_dwordx4 v[54:57], v[6:7], off offset:1344
	s_waitcnt vmcnt(0)
	v_mfma_f32_16x16x32_bf16 v[14:17], v[42:45], v[18:21], v[14:17]
	global_load_dwordx4 v[18:21], v[8:9], off offset:1280
	v_mfma_f32_16x16x32_bf16 v[10:13], v[42:45], v[26:29], v[10:13]
	global_load_dwordx4 v[26:29], v[4:5], off offset:1344
	v_mfma_f32_16x16x32_bf16 v[14:17], v[50:53], v[22:25], v[14:17]
	global_load_dwordx4 v[22:25], v[8:9], off offset:1344
	v_mfma_f32_16x16x32_bf16 v[10:13], v[50:53], v[38:41], v[10:13]
	global_load_dwordx4 v[38:41], v[6:7], off offset:1408
	v_mfma_f32_16x16x32_bf16 v[14:17], v[62:65], v[34:37], v[14:17]
	global_load_dwordx4 v[34:37], v[4:5], off offset:1408
	global_load_dwordx4 v[42:45], v[8:9], off offset:1408
	v_mfma_f32_16x16x32_bf16 v[10:13], v[62:65], v[30:33], v[10:13]
	global_load_dwordx4 v[30:33], v[6:7], off offset:1472
	v_mfma_f32_16x16x32_bf16 v[14:17], v[58:61], v[46:49], v[14:17]
	global_load_dwordx4 v[46:49], v[4:5], off offset:1472
	global_load_dwordx4 v[50:53], v[6:7], off offset:1536
	s_waitcnt vmcnt(0)
	v_mfma_f32_16x16x32_bf16 v[10:13], v[58:61], v[18:21], v[10:13]
	global_load_dwordx4 v[18:21], v[8:9], off offset:1472
	v_mfma_f32_16x16x32_bf16 v[14:17], v[54:57], v[26:29], v[14:17]
	global_load_dwordx4 v[26:29], v[4:5], off offset:1536
	v_mfma_f32_16x16x32_bf16 v[10:13], v[54:57], v[22:25], v[10:13]
	global_load_dwordx4 v[22:25], v[8:9], off offset:1536
	v_mfma_f32_16x16x32_bf16 v[14:17], v[38:41], v[34:37], v[14:17]
	global_load_dwordx4 v[34:37], v[6:7], off offset:1600
	v_mfma_f32_16x16x32_bf16 v[10:13], v[38:41], v[42:45], v[10:13]
	global_load_dwordx4 v[38:41], v[4:5], off offset:1600
	global_load_dwordx4 v[42:45], v[8:9], off offset:1600
	v_mfma_f32_16x16x32_bf16 v[14:17], v[30:33], v[46:49], v[14:17]
	global_load_dwordx4 v[46:49], v[6:7], off offset:1664
	s_waitcnt vmcnt(0)
	v_mfma_f32_16x16x32_bf16 v[10:13], v[30:33], v[18:21], v[10:13]
	global_load_dwordx4 v[18:21], v[4:5], off offset:1664
	global_load_dwordx4 v[30:33], v[8:9], off offset:1664
	v_mfma_f32_16x16x32_bf16 v[14:17], v[50:53], v[26:29], v[14:17]
	global_load_dwordx4 v[26:29], v[6:7], off offset:1728
	v_mfma_f32_16x16x32_bf16 v[10:13], v[50:53], v[22:25], v[10:13]
	global_load_dwordx4 v[22:25], v[4:5], off offset:1728
	global_load_dwordx4 v[50:53], v[8:9], off offset:1728
	v_mfma_f32_16x16x32_bf16 v[14:17], v[34:37], v[38:41], v[14:17]
	global_load_dwordx4 v[38:41], v[6:7], off offset:1792
	v_mfma_f32_16x16x32_bf16 v[10:13], v[34:37], v[42:45], v[10:13]
	global_load_dwordx4 v[34:37], v[4:5], off offset:1792
	global_load_dwordx4 v[42:45], v[8:9], off offset:1792
	s_waitcnt vmcnt(0)
	v_mfma_f32_16x16x32_bf16 v[14:17], v[46:49], v[18:21], v[14:17]
	global_load_dwordx4 v[18:21], v[6:7], off offset:1856
	v_mfma_f32_16x16x32_bf16 v[10:13], v[46:49], v[30:33], v[10:13]
	global_load_dwordx4 v[30:33], v[4:5], off offset:1856
	v_mfma_f32_16x16x32_bf16 v[14:17], v[26:29], v[22:25], v[14:17]
	global_load_dwordx4 v[22:25], v[8:9], off offset:1856
	v_mfma_f32_16x16x32_bf16 v[10:13], v[26:29], v[50:53], v[10:13]
	global_load_dwordx4 v[26:29], v[6:7], off offset:1920
	v_mfma_f32_16x16x32_bf16 v[14:17], v[38:41], v[34:37], v[14:17]
	global_load_dwordx4 v[34:37], v[4:5], off offset:1920
	s_nop 0
	global_load_dwordx4 v[4:7], v[4:5], off offset:1984
	v_mfma_f32_16x16x32_bf16 v[10:13], v[38:41], v[42:45], v[10:13]
	s_waitcnt vmcnt(0)
	v_mfma_f32_16x16x32_bf16 v[14:17], v[18:21], v[30:33], v[14:17]
	global_load_dwordx4 v[30:33], v[8:9], off offset:1920
	v_mfma_f32_16x16x32_bf16 v[10:13], v[18:21], v[22:25], v[10:13]
	global_load_dwordx4 v[18:21], v[8:9], off offset:1984
	v_lshlrev_b64 v[8:9], 6, v[2:3]
	v_lshl_add_u64 v[8:9], s[4:5], 0, v[8:9]
	v_mfma_f32_16x16x32_bf16 v[14:17], v[26:29], v[34:37], v[14:17]
	v_lshl_add_u64 v[8:9], v[8:9], 0, v[0:1]
	v_mfma_f32_16x16x32_bf16 v[4:7], v[70:73], v[4:7], v[14:17]
	s_nop 7
	global_store_dwordx4 v[8:9], v[4:7], off
	s_nop 1
	v_add_u32_e32 v6, 16, v2
	v_ashrrev_i32_e32 v7, 31, v6
	v_lshlrev_b64 v[6:7], 6, v[6:7]
	v_lshl_add_u64 v[6:7], s[4:5], 0, v[6:7]
	v_lshl_add_u64 v[6:7], v[6:7], 0, v[0:1]
	s_waitcnt vmcnt(0)
	v_mfma_f32_16x16x32_bf16 v[2:5], v[26:29], v[30:33], v[10:13]
	v_mfma_f32_16x16x32_bf16 v[0:3], v[70:73], v[18:21], v[2:5]
	s_nop 7
	global_store_dwordx4 v[6:7], v[0:3], off
	s_cmp_eq_u32 s99, 1
	s_cbranch_scc0 .Lg1_done
	s_mov_b32 s99, 2
	s_branch .Lg1_gemm
; __device__ __forceinline__ unsigned xb_ld(unsigned* p)              { return __hip_atomic_load(p, __ATOMIC_RELAXED, __HIP_MEMORY_SCOPE_AGENT); }
; __device__ __forceinline__ void xcd_barrier_complete(unsigned* bar, unsigned x, unsigned& nloc, unsigned& nx) {
;     const unsigned G = gridDim.x * gridDim.y * gridDim.z;
;     unsigned sum, cnt, mine, sp = 0u;
;     for (;;) {
;         sum = 0u; cnt = 0u; mine = 0u;
; #pragma unroll
;         for (unsigned j = 0; j < 16; ++j) { const unsigned c = xb_ld(&bar[XB_XCNT(j)]); sum += c; cnt += (c > 0u) ? 1u : 0u; mine = (j == x) ? c : mine; }
;         if (sum == G) break;
;         __builtin_amdgcn_s_sleep(1);
;         if ((++sp & 255u) == 0u) { if (xb_ld(&bar[XB_TMO])) break; if (sp > XB_SPIN_CAP) { atomicAdd(&bar[XB_TMO], 1u); break; } }
;     }
;     nloc = mine > 0u ? mine : 1u; nx = cnt > 0u ? cnt : 1u;
; __device__ __forceinline__ void xcd_barrier(const XcdBarrier& b) {
;     asm volatile("s_waitcnt vmcnt(0)" ::: "memory");
;     __syncthreads();
;     if (threadIdx.x == 0) {
;         unsigned* bar = b.bar;
;         __builtin_amdgcn_s_waitcnt(0);
;         unsigned nloc = b.st[0], nx = b.st[1];
;         if (nloc == 0u) { xcd_barrier_complete(bar, b.x, nloc, nx); b.st[0] = nloc; b.st[1] = nx; }
.Lg1_done:
.LBB0_79:
	s_cmp_gt_i32 s81, 2
	s_cselect_b64 s[4:5], -1, 0
	s_and_b64 s[0:1], s[0:1], s[4:5]
	s_andn2_b64 vcc, exec, s[0:1]
	s_cbranch_vccnz .LBB0_129
	s_waitcnt vmcnt(0)
	s_waitcnt lgkmcnt(0)
	s_barrier
	s_mov_b64 s[0:1], exec
	v_readlane_b32 s6, v254, 25
	v_readlane_b32 s7, v254, 26
	s_and_b64 s[6:7], s[0:1], s[6:7]
	s_mov_b64 exec, s[6:7]
	s_cbranch_execz .LBB0_128
	s_add_i32 s3, 0, 0x21ff0
	v_mov_b32_e32 v0, s3
	s_waitcnt vmcnt(0) expcnt(0) lgkmcnt(0)
	ds_read_b32 v2, v0
	s_add_i32 s3, 0, 0x21ff4
	v_mov_b32_e32 v0, s3
	ds_read_b32 v0, v0
	s_waitcnt lgkmcnt(1)
	v_cmp_ne_u32_e32 vcc, 0, v2
	s_cbranch_vccnz .LBB0_96
	s_add_u32 s6, s78, 0x193e0200
	s_addc_u32 s7, s79, 0
	s_add_u32 s8, s78, 0x193e0400
	s_addc_u32 s9, s79, 0
	s_add_u32 s10, s78, 0x193e0500
	s_addc_u32 s11, s79, 0
	s_add_u32 s12, s78, 0x193e0600
	s_addc_u32 s13, s79, 0
	s_add_u32 s14, s78, 0x193e0700
	s_addc_u32 s15, s79, 0
	s_add_u32 s16, s78, 0x193e0800
	s_addc_u32 s17, s79, 0
	s_add_u32 s18, s78, 0x193e0900
	s_addc_u32 s19, s79, 0
	s_add_u32 s20, s78, 0x193e0a00
	s_addc_u32 s21, s79, 0
	s_add_u32 s22, s78, 0x193e0b00
	s_addc_u32 s23, s79, 0
	s_add_u32 s24, s78, 0x193e0c00
	s_addc_u32 s25, s79, 0
	s_add_u32 s26, s78, 0x193e0d00
	s_addc_u32 s27, s79, 0
	s_add_u32 s28, s78, 0x193e0e00
	s_addc_u32 s29, s79, 0
	s_add_u32 s30, s78, 0x193e0f00
	s_addc_u32 s31, s79, 0
	s_add_u32 s34, s78, 0x193e1000
	s_addc_u32 s35, s79, 0
	s_add_u32 s36, s78, 0x193e1100
	s_addc_u32 s37, s79, 0
	s_add_u32 s38, s78, 0x193e1200
	v_readlane_b32 s3, v254, 24
	s_addc_u32 s39, s79, 0
	s_mul_i32 s3, s83, s3
	s_add_u32 s40, s78, 0x193e1300
	s_mul_i32 s3, s3, s82
	s_addc_u32 s41, s79, 0
	s_mov_b32 s33, 1
	v_mov_b32_e32 v16, 0
	s_branch .LBB0_84
